# ret_chunk: batch fwd-state chunk loads, K/V/epilogue load hoists; P0 norm loops: gain vector loaded once
# speedup vs baseline: 1.0015x; 1.0015x over previous
.LBB0_66:
	v_mbcnt_lo_u32_b32 v1, -1, 0
	v_mbcnt_hi_u32_b32 v2, -1, v1
	v_and_b32_e32 v1, 64, v2
	v_add_u32_e32 v3, 64, v1
	v_xor_b32_e32 v1, 1, v2
	v_cmp_lt_i32_e32 vcc, v1, v3
	s_waitcnt lgkmcnt(7)
	v_xor_b32_e32 v4, 2, v2
	v_mov_b32_e32 v29, 0
	v_cndmask_b32_e32 v1, v2, v1, vcc
	v_cmp_lt_i32_e32 vcc, v4, v3
	v_mov_b32_e32 v27, v29
	s_mov_b64 s[2:3], 0x3c00000
	v_cndmask_b32_e32 v4, v2, v4, vcc
	v_lshlrev_b32_e32 v37, 2, v4
	v_xor_b32_e32 v4, 4, v2
	v_cmp_lt_i32_e32 vcc, v4, v3
	v_lshl_add_u64 v[30:31], s[44:45], 0, v[28:29]
	v_lshl_add_u64 v[32:33], s[48:49], 0, v[28:29]
	v_cndmask_b32_e32 v4, v2, v4, vcc
	v_lshlrev_b32_e32 v38, 2, v4
	v_xor_b32_e32 v4, 8, v2
	v_cmp_lt_i32_e32 vcc, v4, v3
	v_lshlrev_b32_e32 v1, 2, v1
	v_mov_b32_e32 v36, 0x358637bd
	v_cndmask_b32_e32 v4, v2, v4, vcc
	v_lshlrev_b32_e32 v39, 2, v4
	v_xor_b32_e32 v4, 16, v2
	v_cmp_lt_i32_e32 vcc, v4, v3
	s_mov_b32 s4, s86
	s_nop 0
	v_cndmask_b32_e32 v4, v2, v4, vcc
	v_lshlrev_b32_e32 v40, 2, v4
	v_xor_b32_e32 v4, 32, v2
	v_cmp_lt_i32_e32 vcc, v4, v3
	s_nop 1
	v_cndmask_b32_e32 v2, v2, v4, vcc
	v_lshlrev_b32_e32 v41, 2, v2
	v_lshl_add_u64 v[2:3], s[10:11], 0, v[26:27]
	v_lshl_add_u64 v[34:35], v[2:3], 0, s[2:3]
	s_mov_b32 s2, 0x3a800000
	s_mov_b32 s3, 0x800000
	global_load_dwordx4 v[124:127], v[32:33], off
	global_load_dwordx4 v[128:131], v[32:33], off offset:1024
	global_load_dwordx4 v[132:135], v[32:33], off offset:2048
	global_load_dwordx4 v[136:139], v[32:33], off offset:3072
.LBB0_67:
	s_ashr_i32 s5, s4, 31
	s_lshl_b64 s[10:11], s[4:5], 12
	v_lshl_add_u64 v[6:7], v[30:31], 0, s[10:11]
	s_add_i32 s10, s4, s42
	global_load_dwordx4 v[42:45], v[6:7], off
	global_load_dwordx4 v[18:21], v[6:7], off offset:1024
	s_waitcnt lgkmcnt(6)
	global_load_dwordx4 v[2:5], v[6:7], off offset:3072
	s_waitcnt lgkmcnt(2)
	global_load_dwordx4 v[14:17], v[6:7], off offset:2048
	s_ashr_i32 s11, s10, 31
	s_lshl_b64 s[12:13], s[10:11], 12
	s_waitcnt lgkmcnt(1)
	v_lshl_add_u64 v[10:11], v[30:31], 0, s[12:13]
	global_load_dwordx4 v[46:49], v[10:11], off
	global_load_dwordx4 v[22:25], v[10:11], off offset:1024
	global_load_dwordx4 v[6:9], v[10:11], off offset:3072
	s_waitcnt lgkmcnt(0)
	global_load_dwordx4 v[10:13], v[10:11], off offset:2048
	s_nop 0
	s_lshl_b64 s[4:5], s[4:5], 11
	s_lshl_b64 s[12:13], s[10:11], 11
	s_waitcnt vmcnt(7)
	v_pk_mul_f32 v[54:55], v[44:45], v[44:45]
	v_pk_mul_f32 v[56:57], v[42:43], v[42:43]
	s_waitcnt vmcnt(6)
	v_pk_mul_f32 v[58:59], v[20:21], v[20:21]
	v_pk_mul_f32 v[60:61], v[18:19], v[18:19]
	s_waitcnt vmcnt(4)
	v_mul_f32_e32 v62, v15, v15
	v_mul_f32_e32 v64, v17, v17
	v_pk_mov_b32 v[66:67], v[56:57], v[54:55] op_sel:[1,0]
	v_mov_b32_e32 v57, v55
	s_waitcnt vmcnt(3)
	v_pk_mul_f32 v[54:55], v[48:49], v[48:49]
	v_pk_mul_f32 v[68:69], v[46:47], v[46:47]
	v_pk_mov_b32 v[70:71], v[60:61], v[58:59] op_sel:[1,0]
	v_mov_b32_e32 v61, v59
	s_waitcnt vmcnt(2)
	v_pk_mul_f32 v[58:59], v[24:25], v[24:25]
	v_pk_mul_f32 v[72:73], v[22:23], v[22:23]
	v_mul_f32_e32 v75, v4, v4
	v_mul_f32_e32 v77, v5, v5
	v_pk_fma_f32 v[62:63], v[14:15], v[14:15], v[62:63] op_sel_hi:[1,1,0]
	v_pk_fma_f32 v[64:65], v[16:17], v[16:17], v[64:65] op_sel_hi:[1,1,0]
	v_pk_add_f32 v[56:57], v[66:67], v[56:57]
	v_pk_mov_b32 v[66:67], v[68:69], v[54:55] op_sel:[1,0]
	v_mov_b32_e32 v69, v55
	v_pk_add_f32 v[54:55], v[70:71], v[60:61]
	v_pk_mov_b32 v[60:61], v[72:73], v[58:59] op_sel:[1,0]
	v_mov_b32_e32 v73, v59
	s_waitcnt vmcnt(0)
	v_mul_f32_e32 v74, v11, v11
	v_mul_f32_e32 v76, v13, v13
	v_mov_b32_e32 v63, v75
	v_mov_b32_e32 v65, v77
	v_pk_add_f32 v[66:67], v[66:67], v[68:69]
	v_pk_add_f32 v[60:61], v[60:61], v[72:73]
	v_mul_f32_e32 v27, v2, v2
	v_mul_f32_e32 v29, v3, v3
	v_mul_f32_e32 v78, v6, v6
	v_mul_f32_e32 v79, v7, v7
	v_mul_f32_e32 v80, v8, v8
	v_mul_f32_e32 v81, v9, v9
	v_pk_fma_f32 v[58:59], v[10:11], v[10:11], v[74:75] op_sel_hi:[1,1,0]
	v_pk_fma_f32 v[70:71], v[12:13], v[12:13], v[76:77] op_sel_hi:[1,1,0]
	v_pk_add_f32 v[56:57], v[56:57], v[56:57] op_sel:[0,1] op_sel_hi:[1,0]
	v_pk_add_f32 v[54:55], v[54:55], v[54:55] op_sel:[0,1] op_sel_hi:[1,0]
	v_pk_add_f32 v[62:63], v[62:63], v[64:65]
	v_pk_add_f32 v[64:65], v[66:67], v[66:67] op_sel:[0,1] op_sel_hi:[1,0]
	v_pk_add_f32 v[60:61], v[60:61], v[60:61] op_sel:[0,1] op_sel_hi:[1,0]
	v_mov_b32_e32 v59, v80
	v_mov_b32_e32 v71, v81
	v_mov_b32_e32 v57, v27
	v_mov_b32_e32 v55, v29
	v_mov_b32_e32 v65, v78
	v_mov_b32_e32 v61, v79
	v_pk_add_f32 v[58:59], v[58:59], v[70:71]
	v_pk_add_f32 v[54:55], v[56:57], v[54:55]
	v_pk_add_f32 v[56:57], v[64:65], v[60:61]
	v_pk_add_f32 v[54:55], v[54:55], v[62:63]
	v_pk_add_f32 v[56:57], v[56:57], v[58:59]
	v_mov_b32_e32 v59, v54
	v_mov_b32_e32 v58, v56
	v_mov_b32_e32 v54, v57
	v_pk_add_f32 v[54:55], v[58:59], v[54:55]
	ds_bpermute_b32 v57, v1, v55
	ds_bpermute_b32 v56, v1, v54
	v_lshl_add_u64 v[58:59], v[34:35], 0, s[4:5]
	s_waitcnt lgkmcnt(0)
	v_pk_add_f32 v[54:55], v[54:55], v[56:57]
	ds_bpermute_b32 v57, v37, v55
	ds_bpermute_b32 v56, v37, v54
	s_waitcnt lgkmcnt(0)
	v_pk_add_f32 v[54:55], v[54:55], v[56:57]
	ds_bpermute_b32 v57, v38, v55
	ds_bpermute_b32 v56, v38, v54
	s_waitcnt lgkmcnt(0)
	v_pk_add_f32 v[54:55], v[54:55], v[56:57]
	ds_bpermute_b32 v57, v39, v55
	ds_bpermute_b32 v56, v39, v54
	s_waitcnt lgkmcnt(0)
	v_pk_add_f32 v[54:55], v[54:55], v[56:57]
	ds_bpermute_b32 v57, v40, v55
	ds_bpermute_b32 v56, v40, v54
	s_waitcnt lgkmcnt(0)
	v_pk_add_f32 v[54:55], v[54:55], v[56:57]
	ds_bpermute_b32 v57, v41, v55
	ds_bpermute_b32 v56, v41, v54
	s_waitcnt lgkmcnt(0)
	v_pk_add_f32 v[54:55], v[54:55], v[56:57]
	s_nop 0
	v_pk_fma_f32 v[54:55], v[54:55], s[2:3], v[36:37] op_sel_hi:[1,0,0]
	s_nop 0
	v_mul_f32_e32 v27, 0x4b800000, v55
	v_cmp_gt_f32_e32 vcc, s3, v55
	v_mul_f32_e32 v29, 0x4b800000, v54
	v_cmp_gt_f32_e64 s[4:5], s3, v54
	v_cndmask_b32_e32 v27, v55, v27, vcc
	v_rsq_f32_e32 v27, v27
	v_cndmask_b32_e64 v29, v54, v29, s[4:5]
	v_rsq_f32_e32 v29, v29
	v_lshl_add_u64 v[54:55], v[34:35], 0, s[12:13]
	v_mul_f32_e32 v56, 0x45800000, v27
	v_cndmask_b32_e32 v56, v27, v56, vcc
	v_mul_f32_e32 v57, 0x45800000, v29
	v_cndmask_b32_e64 v60, v29, v57, s[4:5]
	v_pk_mul_f32 v[42:43], v[42:43], v[56:57] op_sel_hi:[1,0]
	v_pk_mul_f32 v[44:45], v[44:45], v[56:57] op_sel_hi:[1,0]
	v_pk_mul_f32 v[46:47], v[46:47], v[60:61] op_sel_hi:[1,0]
	v_pk_mul_f32 v[48:49], v[48:49], v[60:61] op_sel_hi:[1,0]
	v_pk_mul_f32 v[42:43], v[124:125], v[42:43]
	v_pk_mul_f32 v[44:45], v[126:127], v[44:45]
	v_pk_mul_f32 v[46:47], v[124:125], v[46:47]
	v_pk_mul_f32 v[48:49], v[126:127], v[48:49]
	v_cvt_pk_bf16_f32 v42, v42, v43
	v_cvt_pk_bf16_f32 v43, v44, v45
	v_cvt_pk_bf16_f32 v44, v46, v47
	v_cvt_pk_bf16_f32 v45, v48, v49
	global_store_dwordx2 v[58:59], v[42:43], off
	global_store_dwordx2 v[54:55], v[44:45], off
	v_pk_mul_f32 v[18:19], v[18:19], v[56:57] op_sel_hi:[1,0]
	v_pk_mul_f32 v[20:21], v[20:21], v[56:57] op_sel_hi:[1,0]
	v_pk_mul_f32 v[22:23], v[22:23], v[60:61] op_sel_hi:[1,0]
	v_pk_mul_f32 v[24:25], v[24:25], v[60:61] op_sel_hi:[1,0]
	v_pk_mul_f32 v[14:15], v[14:15], v[56:57] op_sel_hi:[1,0]
	v_pk_mul_f32 v[16:17], v[16:17], v[56:57] op_sel_hi:[1,0]
	v_pk_mul_f32 v[10:11], v[10:11], v[60:61] op_sel_hi:[1,0]
	v_pk_mul_f32 v[12:13], v[12:13], v[60:61] op_sel_hi:[1,0]
	v_pk_mul_f32 v[2:3], v[2:3], v[56:57] op_sel_hi:[1,0]
	v_pk_mul_f32 v[4:5], v[4:5], v[56:57] op_sel_hi:[1,0]
	s_add_i32 s4, s10, s42
	v_pk_mul_f32 v[6:7], v[6:7], v[60:61] op_sel_hi:[1,0]
	v_pk_mul_f32 v[8:9], v[8:9], v[60:61] op_sel_hi:[1,0]
	s_cmp_gt_i32 s4, 0xffff
	v_pk_mul_f32 v[18:19], v[128:129], v[18:19]
	v_pk_mul_f32 v[20:21], v[130:131], v[20:21]
	v_pk_mul_f32 v[22:23], v[128:129], v[22:23]
	v_pk_mul_f32 v[24:25], v[130:131], v[24:25]
	v_cvt_pk_bf16_f32 v18, v18, v19
	v_cvt_pk_bf16_f32 v19, v20, v21
	v_cvt_pk_bf16_f32 v20, v22, v23
	v_cvt_pk_bf16_f32 v21, v24, v25
	global_store_dwordx2 v[58:59], v[18:19], off offset:512
	global_store_dwordx2 v[54:55], v[20:21], off offset:512
	v_pk_mul_f32 v[14:15], v[132:133], v[14:15]
	v_pk_mul_f32 v[16:17], v[134:135], v[16:17]
	v_pk_mul_f32 v[10:11], v[132:133], v[10:11]
	v_pk_mul_f32 v[12:13], v[134:135], v[12:13]
	v_cvt_pk_bf16_f32 v14, v14, v15
	v_cvt_pk_bf16_f32 v15, v16, v17
	v_cvt_pk_bf16_f32 v10, v10, v11
	v_cvt_pk_bf16_f32 v11, v12, v13
	global_store_dwordx2 v[58:59], v[14:15], off offset:1024
	global_store_dwordx2 v[54:55], v[10:11], off offset:1024
	v_pk_mul_f32 v[2:3], v[2:3], v[136:137]
	v_pk_mul_f32 v[4:5], v[4:5], v[138:139]
	v_pk_mul_f32 v[6:7], v[6:7], v[136:137]
	v_pk_mul_f32 v[8:9], v[8:9], v[138:139]
	v_cvt_pk_bf16_f32 v2, v2, v3
	v_cvt_pk_bf16_f32 v3, v4, v5
	v_cvt_pk_bf16_f32 v4, v6, v7
	v_cvt_pk_bf16_f32 v5, v8, v9
	global_store_dwordx2 v[58:59], v[2:3], off offset:1536
	global_store_dwordx2 v[54:55], v[4:5], off offset:1536
	s_cbranch_scc0 .LBB0_67
.LBB0_68:
	s_cmpk_gt_i32 s86, 0x1fff
	s_cbranch_scc1 .LBB0_71
	v_mbcnt_lo_u32_b32 v1, -1, 0
	s_waitcnt lgkmcnt(7)
	v_mbcnt_hi_u32_b32 v4, -1, v1
	v_and_b32_e32 v1, 64, v4
	s_waitcnt lgkmcnt(6)
	v_add_u32_e32 v5, 64, v1
	v_xor_b32_e32 v1, 1, v4
	v_cmp_lt_i32_e32 vcc, v1, v5
	v_xor_b32_e32 v6, 2, v4
	s_ashr_i32 s87, s86, 31
	v_cndmask_b32_e32 v1, v4, v1, vcc
	v_cmp_lt_i32_e32 vcc, v6, v5
	s_lshl_b64 s[2:3], s[86:87], 12
	s_add_u32 s2, s46, s2
	v_cndmask_b32_e32 v6, v4, v6, vcc
	s_waitcnt lgkmcnt(5)
	v_lshlrev_b32_e32 v8, 2, v6
	v_xor_b32_e32 v6, 4, v4
	v_cmp_lt_i32_e32 vcc, v6, v5
	v_mov_b32_e32 v29, 0
	s_addc_u32 s3, s47, s3
	v_cndmask_b32_e32 v6, v4, v6, vcc
	s_waitcnt lgkmcnt(4)
	v_lshlrev_b32_e32 v9, 2, v6
	v_xor_b32_e32 v6, 8, v4
	v_cmp_lt_i32_e32 vcc, v6, v5
	s_ashr_i32 s43, s42, 31
	s_lshl_b64 s[4:5], s[86:87], 11
	v_cndmask_b32_e32 v6, v4, v6, vcc
	v_lshlrev_b32_e32 v10, 2, v6
	v_xor_b32_e32 v6, 16, v4
	v_cmp_lt_i32_e32 vcc, v6, v5
	v_mov_b32_e32 v27, v29
	v_lshl_add_u64 v[2:3], s[60:61], 0, v[28:29]
	v_cndmask_b32_e32 v6, v4, v6, vcc
	s_waitcnt lgkmcnt(1)
	v_lshlrev_b32_e32 v11, 2, v6
	v_xor_b32_e32 v6, 32, v4
	v_cmp_lt_i32_e32 vcc, v6, v5
	v_lshlrev_b32_e32 v1, 2, v1
	s_waitcnt lgkmcnt(0)
	v_mov_b32_e32 v13, 0x358637bd
	v_cndmask_b32_e32 v4, v4, v6, vcc
	v_lshlrev_b32_e32 v12, 2, v4
	v_lshl_add_u64 v[4:5], s[2:3], 0, v[28:29]
	s_mov_b64 s[2:3], 0xc00
	v_lshl_add_u64 v[4:5], v[4:5], 0, s[2:3]
	s_lshl_b64 s[2:3], s[42:43], 12
	s_add_u32 s4, s8, s4
	s_addc_u32 s5, s9, s5
	s_add_u32 s4, s80, s4
	s_addc_u32 s5, s81, s5
	v_lshl_add_u64 v[6:7], s[4:5], 0, v[26:27]
	s_mov_b64 s[4:5], 0xbc00400
	v_lshl_add_u64 v[6:7], v[6:7], 0, s[4:5]
	s_lshl_b64 s[4:5], s[42:43], 11
	s_mov_b32 s8, 0x800000
	s_mov_b32 s9, s86
	global_load_dwordx4 v[140:143], v[2:3], off
	global_load_dwordx4 v[144:147], v[2:3], off offset:1024
	global_load_dwordx4 v[148:151], v[2:3], off offset:2048
	global_load_dwordx4 v[152:155], v[2:3], off offset:3072
.LBB0_70:
	global_load_dwordx4 v[14:17], v[4:5], off offset:-3072
	global_load_dwordx4 v[18:21], v[4:5], off offset:-2048
	global_load_dwordx4 v[22:25], v[4:5], off offset:-1024
	global_load_dwordx4 v[26:29], v[4:5], off
	s_add_i32 s9, s9, s42
	v_lshl_add_u64 v[4:5], v[4:5], 0, s[2:3]
	s_cmpk_gt_i32 s9, 0x1fff
	s_waitcnt vmcnt(3)
	v_pk_mul_f32 v[34:35], v[16:17], v[16:17]
	v_pk_mul_f32 v[36:37], v[14:15], v[14:15]
	s_waitcnt vmcnt(2)
	v_pk_mul_f32 v[38:39], v[20:21], v[20:21]
	v_pk_mul_f32 v[40:41], v[18:19], v[18:19]
	v_pk_mov_b32 v[46:47], v[36:37], v[34:35] op_sel:[1,0]
	v_mov_b32_e32 v37, v35
	v_pk_mov_b32 v[34:35], v[40:41], v[38:39] op_sel:[1,0]
	v_mov_b32_e32 v41, v39
	s_waitcnt vmcnt(0)
	v_mul_f32_e32 v45, v26, v26
	v_mul_f32_e32 v42, v23, v23
	v_mul_f32_e32 v44, v25, v25
	v_pk_add_f32 v[36:37], v[46:47], v[36:37]
	v_pk_add_f32 v[34:35], v[34:35], v[40:41]
	v_mul_f32_e32 v48, v27, v27
	v_mul_f32_e32 v49, v28, v28
	v_mul_f32_e32 v50, v29, v29
	v_pk_fma_f32 v[38:39], v[22:23], v[22:23], v[42:43] op_sel_hi:[1,1,0]
	v_pk_fma_f32 v[42:43], v[24:25], v[24:25], v[44:45] op_sel_hi:[1,1,0]
	v_pk_add_f32 v[36:37], v[36:37], v[36:37] op_sel:[0,1] op_sel_hi:[1,0]
	v_pk_add_f32 v[34:35], v[34:35], v[34:35] op_sel:[0,1] op_sel_hi:[1,0]
	v_mov_b32_e32 v39, v49
	v_mov_b32_e32 v43, v50
	v_mov_b32_e32 v37, v45
	v_mov_b32_e32 v35, v48
	v_pk_add_f32 v[38:39], v[38:39], v[42:43]
	v_pk_add_f32 v[34:35], v[36:37], v[34:35]
	s_nop 0
	v_pk_add_f32 v[34:35], v[34:35], v[38:39]
	s_nop 0
	v_add_f32_e32 v34, v34, v35
	ds_bpermute_b32 v35, v1, v34
	s_waitcnt lgkmcnt(0)
	v_add_f32_e32 v34, v34, v35
	ds_bpermute_b32 v35, v8, v34
	s_waitcnt lgkmcnt(0)
	v_add_f32_e32 v34, v34, v35
	ds_bpermute_b32 v35, v9, v34
	s_waitcnt lgkmcnt(0)
	v_add_f32_e32 v34, v34, v35
	ds_bpermute_b32 v35, v10, v34
	s_waitcnt lgkmcnt(0)
	v_add_f32_e32 v34, v34, v35
	ds_bpermute_b32 v35, v11, v34
	s_waitcnt lgkmcnt(0)
	v_add_f32_e32 v34, v34, v35
	ds_bpermute_b32 v35, v12, v34
	s_waitcnt lgkmcnt(0)
	v_add_f32_e32 v34, v34, v35
	v_fmamk_f32 v34, v34, 0x3a800000, v13
	v_mul_f32_e32 v35, 0x4b800000, v34
	v_cmp_gt_f32_e32 vcc, s8, v34
	s_nop 1
	v_cndmask_b32_e32 v34, v34, v35, vcc
	v_rsq_f32_e32 v34, v34
	s_nop 0
	v_mul_f32_e32 v35, 0x45800000, v34
	v_cndmask_b32_e32 v34, v34, v35, vcc
	v_pk_mul_f32 v[14:15], v[14:15], v[34:35] op_sel_hi:[1,0]
	v_pk_mul_f32 v[16:17], v[16:17], v[34:35] op_sel_hi:[1,0]
	v_pk_mul_f32 v[14:15], v[140:141], v[14:15]
	v_pk_mul_f32 v[16:17], v[142:143], v[16:17]
	v_cvt_pk_bf16_f32 v14, v14, v15
	v_cvt_pk_bf16_f32 v15, v16, v17
	global_store_dwordx2 v[6:7], v[14:15], off offset:-1024
	v_pk_mul_f32 v[18:19], v[18:19], v[34:35] op_sel_hi:[1,0]
	v_pk_mul_f32 v[20:21], v[20:21], v[34:35] op_sel_hi:[1,0]
	v_pk_mul_f32 v[14:15], v[144:145], v[18:19]
	v_pk_mul_f32 v[16:17], v[146:147], v[20:21]
	v_cvt_pk_bf16_f32 v14, v14, v15
	v_cvt_pk_bf16_f32 v15, v16, v17
	global_store_dwordx2 v[6:7], v[14:15], off offset:-512
	v_pk_mul_f32 v[18:19], v[22:23], v[34:35] op_sel_hi:[1,0]
	v_pk_mul_f32 v[20:21], v[24:25], v[34:35] op_sel_hi:[1,0]
	v_pk_mul_f32 v[14:15], v[148:149], v[18:19]
	v_pk_mul_f32 v[16:17], v[150:151], v[20:21]
	v_cvt_pk_bf16_f32 v14, v14, v15
	v_cvt_pk_bf16_f32 v15, v16, v17
	global_store_dwordx2 v[6:7], v[14:15], off
	v_pk_mul_f32 v[18:19], v[26:27], v[34:35] op_sel_hi:[1,0]
	v_pk_mul_f32 v[20:21], v[28:29], v[34:35] op_sel_hi:[1,0]
	v_pk_mul_f32 v[14:15], v[152:153], v[18:19]
	v_pk_mul_f32 v[16:17], v[154:155], v[20:21]
	v_cvt_pk_bf16_f32 v14, v14, v15
	v_cvt_pk_bf16_f32 v15, v16, v17
	global_store_dwordx2 v[6:7], v[14:15], off offset:512
	v_lshl_add_u64 v[6:7], v[6:7], 0, s[4:5]
	s_cbranch_scc0 .LBB0_70

.LBB0_439:
	s_add_i32 s98, s0, 0
	s_max_i32 s98, s98, 0
	s_lshl_b32 s98, s98, 15
	s_mov_b32 s99, 0
	v_lshl_add_u64 v[216:217], v[2:3], 0, s[98:99]
	global_load_dwordx4 v[184:187], v[216:217], off offset:16
	global_load_dwordx4 v[188:191], v[216:217], off
	s_add_i32 s98, s0, 1
	s_max_i32 s98, s98, 0
	s_lshl_b32 s98, s98, 15
	s_mov_b32 s99, 0
	v_lshl_add_u64 v[216:217], v[2:3], 0, s[98:99]
	global_load_dwordx4 v[192:195], v[216:217], off offset:16
	global_load_dwordx4 v[196:199], v[216:217], off
	s_add_i32 s98, s0, 2
	s_max_i32 s98, s98, 0
	s_lshl_b32 s98, s98, 15
	s_mov_b32 s99, 0
	v_lshl_add_u64 v[216:217], v[2:3], 0, s[98:99]
	global_load_dwordx4 v[200:203], v[216:217], off offset:16
	global_load_dwordx4 v[204:207], v[216:217], off
	s_add_i32 s98, s0, 3
	s_max_i32 s98, s98, 0
	s_lshl_b32 s98, s98, 15
	s_mov_b32 s99, 0
	v_lshl_add_u64 v[216:217], v[2:3], 0, s[98:99]
	global_load_dwordx4 v[208:211], v[216:217], off offset:16
	global_load_dwordx4 v[212:215], v[216:217], off
	s_max_i32 s1, s0, 0
	s_lshl_b32 s48, s1, 1
	s_lshl_b64 s[6:7], s[48:49], 14
	s_add_i32 s1, s0, 1
	s_max_i32 s1, s1, 0
	s_lshl_b32 s48, s1, 1
	s_lshl_b64 s[6:7], s[48:49], 14
	s_max_i32 s1, s0, -2
	s_lshl_b32 s1, s1, 1
	s_add_i32 s48, s1, 4
	s_max_i32 s1, s0, -3
	s_lshl_b32 s1, s1, 1
	s_waitcnt vmcnt(6)
	v_lshlrev_b32_e32 v13, 16, v184
	v_lshlrev_b32_e32 v25, 16, v188
	v_and_b32_e32 v37, 0xffff0000, v188
	v_lshlrev_b32_e32 v23, 16, v189
	v_and_b32_e32 v35, 0xffff0000, v189
	v_lshlrev_b32_e32 v21, 16, v190
	v_and_b32_e32 v33, 0xffff0000, v190
	v_lshlrev_b32_e32 v11, 16, v191
	v_and_b32_e32 v31, 0xffff0000, v191
	v_and_b32_e32 v29, 0xffff0000, v184
	v_lshlrev_b32_e32 v15, 16, v185
	v_and_b32_e32 v27, 0xffff0000, v185
	v_lshlrev_b32_e32 v17, 16, v186
	v_and_b32_e32 v9, 0xffff0000, v186
	v_lshlrev_b32_e32 v19, 16, v187
	v_and_b32_e32 v5, 0xffff0000, v187
	s_lshl_b64 s[6:7], s[48:49], 14
	s_add_i32 s48, s1, 6
	s_waitcnt vmcnt(4)
	v_lshlrev_b32_e32 v78, 16, v192
	v_lshlrev_b32_e32 v86, 16, v196
	v_and_b32_e32 v85, 0xffff0000, v196
	v_lshlrev_b32_e32 v84, 16, v197
	v_and_b32_e32 v83, 0xffff0000, v197
	v_lshlrev_b32_e32 v82, 16, v198
	v_and_b32_e32 v81, 0xffff0000, v198
	v_lshlrev_b32_e32 v80, 16, v199
	v_and_b32_e32 v79, 0xffff0000, v199
	v_and_b32_e32 v77, 0xffff0000, v192
	v_lshlrev_b32_e32 v76, 16, v193
	v_and_b32_e32 v75, 0xffff0000, v193
	v_lshlrev_b32_e32 v74, 16, v194
	v_and_b32_e32 v73, 0xffff0000, v194
	v_lshlrev_b32_e32 v72, 16, v195
	v_and_b32_e32 v71, 0xffff0000, v195
	s_lshl_b64 s[6:7], s[48:49], 14
	s_cmp_lt_i32 s0, 0
	s_waitcnt vmcnt(2)
	v_lshlrev_b32_e32 v90, 16, v200
	v_lshlrev_b32_e32 v94, 16, v204
	v_and_b32_e32 v54, 0xffff0000, v204
	v_lshlrev_b32_e32 v93, 16, v205
	v_and_b32_e32 v53, 0xffff0000, v205
	v_lshlrev_b32_e32 v92, 16, v206
	v_and_b32_e32 v52, 0xffff0000, v206
	v_lshlrev_b32_e32 v91, 16, v207
	v_and_b32_e32 v51, 0xffff0000, v207
	v_and_b32_e32 v50, 0xffff0000, v200
	v_lshlrev_b32_e32 v89, 16, v201
	v_and_b32_e32 v49, 0xffff0000, v201
	v_lshlrev_b32_e32 v88, 16, v202
	v_and_b32_e32 v48, 0xffff0000, v202
	v_lshlrev_b32_e32 v87, 16, v203
	v_and_b32_e32 v0, 0xffff0000, v203
	s_cselect_b64 s[6:7], -1, 0
	v_cndmask_b32_e64 v7, 1.0, 0, s[6:7]
	s_cmp_lt_i32 s0, -2
	s_cselect_b64 s[6:7], -1, 0
	s_cmp_lt_i32 s0, -3
	s_waitcnt vmcnt(0)
	v_lshlrev_b32_e32 v62, 16, v208
	v_and_b32_e32 v61, 0xffff0000, v208
	v_mul_f32_e32 v38, v7, v25
	v_lshlrev_b32_e32 v66, 16, v214
	v_and_b32_e32 v65, 0xffff0000, v214
	v_lshlrev_b32_e32 v64, 16, v215
	v_and_b32_e32 v63, 0xffff0000, v215
	v_pk_fma_f32 v[44:45], v[6:7], v[24:25], v[38:39] op_sel_hi:[1,1,0]
	v_mul_f32_e32 v24, v7, v37
	v_lshlrev_b32_e32 v70, 16, v212
	v_and_b32_e32 v69, 0xffff0000, v212
	v_lshlrev_b32_e32 v68, 16, v213
	v_and_b32_e32 v67, 0xffff0000, v213
	v_pk_fma_f32 v[42:43], v[6:7], v[36:37], v[24:25] op_sel_hi:[1,1,0]
	v_mul_f32_e32 v24, v7, v23
	v_lshlrev_b32_e32 v58, 16, v210
	v_and_b32_e32 v57, 0xffff0000, v210
	v_lshlrev_b32_e32 v56, 16, v211
	v_and_b32_e32 v55, 0xffff0000, v211
	v_pk_fma_f32 v[40:41], v[6:7], v[22:23], v[24:25] op_sel_hi:[1,1,0]
	v_mul_f32_e32 v22, v7, v35
	v_lshlrev_b32_e32 v60, 16, v209
	v_and_b32_e32 v59, 0xffff0000, v209
	v_pk_fma_f32 v[38:39], v[6:7], v[34:35], v[22:23] op_sel_hi:[1,1,0]
	v_mul_f32_e32 v22, v7, v21
	v_pk_fma_f32 v[36:37], v[6:7], v[20:21], v[22:23] op_sel_hi:[1,1,0]
	v_mul_f32_e32 v20, v7, v33
	v_pk_fma_f32 v[34:35], v[6:7], v[32:33], v[20:21] op_sel_hi:[1,1,0]
	v_mul_f32_e32 v20, v7, v11
	v_pk_fma_f32 v[32:33], v[6:7], v[10:11], v[20:21] op_sel_hi:[1,1,0]
	v_mul_f32_e32 v10, v7, v31
	v_mul_f32_e32 v20, v7, v13
	v_pk_fma_f32 v[10:11], v[6:7], v[30:31], v[10:11] op_sel_hi:[1,1,0]
	v_pk_fma_f32 v[30:31], v[6:7], v[12:13], v[20:21] op_sel_hi:[1,1,0]
	v_mul_f32_e32 v12, v7, v29
	v_mul_f32_e32 v20, v7, v15
	v_pk_fma_f32 v[12:13], v[6:7], v[28:29], v[12:13] op_sel_hi:[1,1,0]
	v_pk_fma_f32 v[28:29], v[6:7], v[14:15], v[20:21] op_sel_hi:[1,1,0]
	v_mul_f32_e32 v14, v7, v27
	v_mul_f32_e32 v20, v7, v17
	v_pk_fma_f32 v[14:15], v[6:7], v[26:27], v[14:15] op_sel_hi:[1,1,0]
	v_pk_fma_f32 v[26:27], v[6:7], v[16:17], v[20:21] op_sel_hi:[1,1,0]
	v_mul_f32_e32 v16, v7, v9
	v_pk_fma_f32 v[16:17], v[6:7], v[8:9], v[16:17] op_sel_hi:[1,1,0]
	v_mul_f32_e32 v8, v7, v19
	v_mov_b32_e32 v45, v86
	v_pk_fma_f32 v[24:25], v[6:7], v[18:19], v[8:9] op_sel_hi:[1,1,0]
	v_mul_f32_e32 v18, v7, v86
	v_mul_f32_e32 v8, v7, v5
	v_pk_fma_f32 v[18:19], v[6:7], v[44:45], v[18:19] op_sel_hi:[1,1,0]
	v_pk_fma_f32 v[8:9], v[6:7], v[4:5], v[8:9] op_sel_hi:[1,1,0]
	v_cndmask_b32_e64 v5, 1.0, 0, s[6:7]
	v_mov_b32_e32 v4, v6
	v_mov_b32_e32 v19, v94
	v_pk_mul_f32 v[18:19], v[4:5], v[18:19]
	v_mov_b32_e32 v43, v85
	v_add_f32_e32 v44, v18, v19
	v_mul_f32_e32 v18, v7, v85
	v_mov_b32_e32 v41, v84
	v_pk_fma_f32 v[22:23], v[6:7], v[42:43], v[18:19] op_sel_hi:[1,1,0]
	v_mul_f32_e32 v18, v7, v84
	v_pk_fma_f32 v[18:19], v[6:7], v[40:41], v[18:19] op_sel_hi:[1,1,0]
	v_mov_b32_e32 v39, v83
	v_mov_b32_e32 v19, v93
	v_pk_mul_f32 v[18:19], v[4:5], v[18:19]
	v_mov_b32_e32 v37, v82
	v_add_f32_e32 v40, v18, v19
	v_mul_f32_e32 v18, v7, v83
	v_pk_fma_f32 v[20:21], v[6:7], v[38:39], v[18:19] op_sel_hi:[1,1,0]
	v_mul_f32_e32 v18, v7, v82
	v_pk_fma_f32 v[18:19], v[6:7], v[36:37], v[18:19] op_sel_hi:[1,1,0]
	v_mov_b32_e32 v35, v81
	v_mov_b32_e32 v19, v92
	v_pk_mul_f32 v[18:19], v[4:5], v[18:19]
	v_mov_b32_e32 v33, v80
	v_add_f32_e32 v36, v18, v19
	v_mul_f32_e32 v18, v7, v81
	v_pk_fma_f32 v[18:19], v[6:7], v[34:35], v[18:19] op_sel_hi:[1,1,0]
	v_mul_f32_e32 v34, v7, v80
	v_pk_fma_f32 v[32:33], v[6:7], v[32:33], v[34:35] op_sel_hi:[1,1,0]
	v_mov_b32_e32 v11, v79
	v_mov_b32_e32 v33, v91
	v_pk_mul_f32 v[32:33], v[4:5], v[32:33]
	v_mov_b32_e32 v31, v78
	v_add_f32_e32 v33, v32, v33
	v_mul_f32_e32 v32, v7, v79
	v_pk_fma_f32 v[10:11], v[6:7], v[10:11], v[32:33] op_sel_hi:[1,1,0]
	v_mul_f32_e32 v32, v7, v78
	v_pk_fma_f32 v[30:31], v[6:7], v[30:31], v[32:33] op_sel_hi:[1,1,0]
	v_mov_b32_e32 v13, v77
	v_mov_b32_e32 v31, v90
	v_pk_mul_f32 v[30:31], v[4:5], v[30:31]
	v_mov_b32_e32 v29, v76
	v_add_f32_e32 v31, v30, v31
	v_mul_f32_e32 v30, v7, v77
	v_pk_fma_f32 v[12:13], v[6:7], v[12:13], v[30:31] op_sel_hi:[1,1,0]
	v_mul_f32_e32 v30, v7, v76
	v_pk_fma_f32 v[28:29], v[6:7], v[28:29], v[30:31] op_sel_hi:[1,1,0]
	v_mov_b32_e32 v15, v75
	v_mov_b32_e32 v29, v89
	v_pk_mul_f32 v[28:29], v[4:5], v[28:29]
	v_mov_b32_e32 v27, v74
	v_add_f32_e32 v29, v28, v29
	v_mul_f32_e32 v28, v7, v75
	v_pk_fma_f32 v[14:15], v[6:7], v[14:15], v[28:29] op_sel_hi:[1,1,0]
	v_mul_f32_e32 v28, v7, v74
	v_pk_fma_f32 v[26:27], v[6:7], v[26:27], v[28:29] op_sel_hi:[1,1,0]
	v_mov_b32_e32 v17, v73
	v_mov_b32_e32 v27, v88
	v_pk_mul_f32 v[26:27], v[4:5], v[26:27]
	v_mov_b32_e32 v25, v72
	v_add_f32_e32 v30, v26, v27
	v_mul_f32_e32 v26, v7, v73
	v_pk_fma_f32 v[16:17], v[6:7], v[16:17], v[26:27] op_sel_hi:[1,1,0]
	v_mul_f32_e32 v26, v7, v72
	v_pk_fma_f32 v[24:25], v[6:7], v[24:25], v[26:27] op_sel_hi:[1,1,0]
	v_mov_b32_e32 v23, v54
	v_mov_b32_e32 v25, v87
	v_pk_mul_f32 v[24:25], v[4:5], v[24:25]
	v_mul_f32_e32 v28, v5, v54
	v_mov_b32_e32 v9, v71
	v_mov_b32_e32 v21, v53
	v_add_f32_e32 v32, v24, v25
	v_mul_f32_e32 v24, v7, v71
	s_cselect_b64 s[6:7], -1, 0
	v_pk_fma_f32 v[22:23], v[4:5], v[22:23], v[28:29] op_sel_hi:[1,1,0]
	v_mul_f32_e32 v28, v5, v53
	v_mov_b32_e32 v19, v52
	v_pk_fma_f32 v[8:9], v[6:7], v[8:9], v[24:25] op_sel_hi:[1,1,0]
	v_cndmask_b32_e64 v7, 1.0, 0, s[6:7]
	v_mov_b32_e32 v23, v69
	v_pk_fma_f32 v[20:21], v[4:5], v[20:21], v[28:29] op_sel_hi:[1,1,0]
	v_mul_f32_e32 v28, v5, v52
	v_mov_b32_e32 v11, v51
	v_pk_mul_f32 v[22:23], v[6:7], v[22:23]
	v_mov_b32_e32 v21, v67
	v_pk_fma_f32 v[18:19], v[4:5], v[18:19], v[28:29] op_sel_hi:[1,1,0]
	v_mul_f32_e32 v28, v5, v51
	v_mov_b32_e32 v13, v50
	v_mul_f32_e32 v24, v6, v44
	v_mul_f32_e32 v26, v7, v70
	v_mov_b32_e32 v25, v22
	v_mov_b32_e32 v27, v23
	v_pk_mul_f32 v[20:21], v[6:7], v[20:21]
	v_mov_b32_e32 v19, v65
	v_pk_fma_f32 v[10:11], v[4:5], v[10:11], v[28:29] op_sel_hi:[1,1,0]
	v_mul_f32_e32 v28, v5, v50
	v_mov_b32_e32 v15, v49
	v_pk_add_f32 v[24:25], v[24:25], v[26:27]
	v_mul_f32_e32 v22, v6, v40
	v_mul_f32_e32 v26, v7, v68
	v_mov_b32_e32 v23, v20
	v_mov_b32_e32 v27, v21
	v_pk_mul_f32 v[18:19], v[6:7], v[18:19]
	v_mov_b32_e32 v11, v63
	v_pk_fma_f32 v[12:13], v[4:5], v[12:13], v[28:29] op_sel_hi:[1,1,0]
	v_mul_f32_e32 v28, v5, v49
	v_mov_b32_e32 v17, v48
	v_pk_add_f32 v[22:23], v[22:23], v[26:27]
	v_mul_f32_e32 v20, v6, v36
	v_mul_f32_e32 v26, v7, v66
	v_mov_b32_e32 v21, v18
	v_mov_b32_e32 v27, v19
	v_pk_mul_f32 v[10:11], v[6:7], v[10:11]
	v_mov_b32_e32 v13, v61
	v_pk_fma_f32 v[14:15], v[4:5], v[14:15], v[28:29] op_sel_hi:[1,1,0]
	v_mul_f32_e32 v28, v5, v48
	v_mov_b32_e32 v9, v0
	v_pk_add_f32 v[20:21], v[20:21], v[26:27]
	v_mul_f32_e32 v18, v6, v33
	v_mul_f32_e32 v26, v7, v64
	v_mov_b32_e32 v19, v10
	v_mov_b32_e32 v27, v11
	v_pk_mul_f32 v[12:13], v[6:7], v[12:13]
	v_mov_b32_e32 v15, v59
	v_pk_fma_f32 v[16:17], v[4:5], v[16:17], v[28:29] op_sel_hi:[1,1,0]
	v_mul_f32_e32 v0, v5, v0
	v_pk_add_f32 v[10:11], v[18:19], v[26:27]
	v_mul_f32_e32 v18, v6, v31
	v_mul_f32_e32 v26, v7, v62
	v_mov_b32_e32 v19, v12
	v_mov_b32_e32 v27, v13
	v_pk_mul_f32 v[14:15], v[6:7], v[14:15]
	v_mov_b32_e32 v17, v57
	v_pk_fma_f32 v[4:5], v[4:5], v[8:9], v[0:1] op_sel_hi:[1,1,0]
	v_pk_add_f32 v[12:13], v[18:19], v[26:27]
	v_mul_f32_e32 v18, v6, v29
	v_mul_f32_e32 v26, v7, v60
	v_mov_b32_e32 v19, v14
	v_mov_b32_e32 v27, v15
	v_pk_mul_f32 v[16:17], v[6:7], v[16:17]
	v_mov_b32_e32 v5, v55
	v_pk_add_f32 v[14:15], v[18:19], v[26:27]
	v_mul_f32_e32 v18, v6, v30
	v_mul_f32_e32 v26, v7, v58
	v_mov_b32_e32 v19, v16
	v_mov_b32_e32 v27, v17
	v_pk_mul_f32 v[4:5], v[6:7], v[4:5]
	v_pk_add_f32 v[16:17], v[18:19], v[26:27]
	v_mul_f32_e32 v18, v6, v32
	v_mul_f32_e32 v26, v7, v56
	v_mov_b32_e32 v19, v4
	v_mov_b32_e32 v27, v5
	v_pk_add_f32 v[18:19], v[18:19], v[26:27]
	s_add_i32 s0, s0, 4
	v_mov_b32_e32 v36, v25
	v_mov_b32_e32 v34, v23
	v_mov_b32_e32 v32, v21
	v_mov_b32_e32 v30, v11
	v_mov_b32_e32 v28, v13
	v_mov_b32_e32 v26, v15
	v_mov_b32_e32 v8, v17
	v_mov_b32_e32 v4, v19
	s_cmp_ge_i32 s0, s68
	s_cbranch_scc0 .LBB0_439
	s_mov_b64 s[0:1], 0
	s_branch .LBB0_442
